# ssd_out C x B^T blocks and ret_local k-steps: LDS fragments read up front with counted waits
# speedup vs baseline: 1.0088x; 1.0034x over previous
; DI void unpack8(uint4 v, float* f) { f[0] = bflo(v.x); f[1] = bfhi(v.x); f[2] = bflo(v.y); f[3] = bfhi(v.y); f[4] = bflo(v.z); f[5] = bfhi(v.z); f[6] = bflo(v.w); f[7] = bfhi(v.w); }
; DI float ex2(float x) { return __builtin_amdgcn_exp2f(x); }
; DI void norm_unit(const Params& p, int layer, int half, int nu, int tid) { norm_rows(p, layer, half * HROWS + nu * 64, 64, 0, 8, tid); }
; #define otid() otid_(wbase)
; DI void ret_local_unit(const Params& p, int hf, int bl, int c, int hd, unsigned char* shm, int tid) {
;   unsigned char* wsb = ows(p);
;   bf16_t* sK = (bf16_t*)shm; bf16_t* sV = sK + 128 * LD;
;   const bf16_t* projb = (const bf16_t*)(wsb + WS_PROJ) + (size_t)bl * SEQ * NP;
;   const float2* cs = (const float2*)(wsb + WS_CS) + (size_t)((hf * 2 + bl) * SEQ + c * 128) * 64;
;   const float lg = logf(1.0f - ex2(-5.0f - (float)hd));
; #pragma unroll
;   for (int it = 0; it < 2; ++it) {
;     const int idx = tid + it * NTHR, j = idx >> 3, dg = idx & 7;
;     const bf16_t* base = projb + (size_t)(c * 128 + j) * NP;
;     float k1[8], k2[8]; unpack8(*(const uint4*)(base + C_RK + hd * 128 + dg * 8), k1); unpack8(*(const uint4*)(base + C_RK + hd * 128 + 64 + dg * 8), k2);
;     const float w = __expf(lg * (float)(127 - j)) * 0.08838834764831845f;
; __global__ void __launch_bounds__(NTHR) mega(Params p) {
;     ...
;           if (u >= 784 + n_fill) break;
;           if (u >= 16 && u < 16 + n_fill) { norm_unit(p, layer, 1, u - 16, otid()); continue; }
;           if (u >= 16) u -= n_fill;
;           if (u < 16) fox_cumsum_unit(p, hf, u >> 3, u & 7, shm, otid());
;           else if (u < 272) { const int k = u - 16; ssd_local_unit(p, layer, hf, k >> 7, (k >> 1) & 63, k & 1, shm, otid()); }
;           else { const int k = u - 272; ret_local_unit(p, hf, k >> 8, (k >> 2) & 63, k & 3, shm, otid()); }
.LBB0_241:
	s_or_b64 exec, exec, s[0:1]
	s_waitcnt lgkmcnt(0)
	s_barrier
	ds_read_b32 v0, v161 offset:16
	s_mov_b64 s[0:1], -1
	s_waitcnt lgkmcnt(0)
	v_cmp_le_i32_e32 vcc, s56, v0
	v_readfirstlane_b32 s58, v0
	s_cbranch_vccnz .LBB0_236
	s_cmp_gt_i32 s58, 15
	s_cselect_b64 s[0:1], -1, 0
	s_cmp_lt_i32 s58, s57
	s_cselect_b64 s[4:5], -1, 0
	s_and_b64 s[4:5], s[0:1], s[4:5]
	s_andn2_b64 vcc, exec, s[4:5]
	s_mov_b64 s[4:5], -1
	s_cbranch_vccz .LBB0_353
	s_and_b64 s[0:1], s[0:1], exec
	s_cselect_b32 s0, s13, 0
	s_sub_i32 s24, s58, s0
	s_cmp_gt_i32 s24, 15
	s_mov_b64 s[0:1], -1
	s_cbranch_scc0 .LBB0_312
	s_cmpk_gt_u32 s24, 0x10f
	s_cbranch_scc0 .LBB0_246
	s_cmpk_gt_u32 s24, 0x30f
	s_cbranch_scc1 .Lkmx_unit
	s_add_i32 s8, s24, 0xfffffef0
	s_lshr_b32 s4, s8, 8
	s_mul_i32 s2, s4, 0x3400000
	s_bfe_u32 s10, s8, 0x60002
	s_and_b32 s9, s58, 3
	s_lshl_b64 s[0:1], s[2:3], 1
	s_add_u32 s6, s38, s0
	s_addc_u32 s7, s39, s1
	s_lshl_b32 s0, s4, 13
	v_cvt_f32_ubyte0_e32 v0, s9
	s_add_i32 s0, s0, s68
	s_lshl_b32 s11, s10, 7
	v_sub_f32_e32 v0, 0xc0a00000, v0
	s_or_b32 s0, s0, s11
	v_exp_f32_e32 v0, v0
	s_lshl_b32 s2, s0, 6
	s_lshl_b64 s[0:1], s[2:3], 3
	v_readlane_b32 s2, v252, 45
	s_add_u32 s4, s2, s0
	v_readlane_b32 s0, v252, 46
	s_addc_u32 s5, s0, s1
	v_sub_f32_e32 v0, 1.0, v0
	s_mov_b32 s0, 0x800000
	v_cmp_gt_f32_e32 vcc, s0, v0
	s_and_b64 s[0:1], vcc, exec
	s_cselect_b32 s0, 32, 0
	v_ldexp_f32 v0, v0, s0
	v_log_f32_e32 v0, v0
	s_mov_b32 s0, 0x3f317217
	v_mov_b32_e32 v18, v163
	v_mul_f32_e32 v1, 0x3f317217, v0
	v_fma_f32 v1, v0, s0, -v1
	v_fmac_f32_e32 v1, 0x3377d1cf, v0
	s_mov_b32 s0, 0x7f800000
	v_fmac_f32_e32 v1, 0x3f317217, v0
	v_cmp_lt_f32_e64 s[0:1], |v0|, s0
	v_ashrrev_i32_e32 v13, 3, v18
	v_mov_b64_e32 v[14:15], s[6:7]
	v_cndmask_b32_e64 v0, v0, v1, s[0:1]
	v_cndmask_b32_e32 v1, 0, v201, vcc
	v_sub_f32_e32 v21, v0, v1
	v_and_b32_e32 v0, 7, v18
	v_lshlrev_b32_e32 v20, 3, v0
	v_lshlrev_b32_e32 v160, 4, v0
	v_lshlrev_b32_e32 v12, 5, v0
	v_add_u32_e32 v0, s11, v13
	v_mad_i64_i32 v[0:1], s[0:1], v0, s65, v[14:15]
	s_lshl_b32 s2, s9, 8
	v_lshl_add_u64 v[16:17], v[0:1], 0, s[2:3]
	v_lshl_add_u64 v[4:5], v[16:17], 0, v[160:161]
	v_lshl_add_u64 v[208:209], v[16:17], 0, v[160:161]
	global_load_dwordx4 v[100:103], v[208:209], off offset:1024
	global_load_dwordx4 v[104:107], v[208:209], off offset:1152
	v_lshl_or_b32 v210, v13, 6, v20
	v_mov_b32_e32 v211, v161
	v_lshl_add_u64 v[210:211], v[210:211], 3, s[4:5]
	global_load_dwordx4 v[108:111], v[210:211], off offset:48
	global_load_dwordx4 v[112:115], v[210:211], off offset:32
	global_load_dwordx4 v[116:119], v[210:211], off offset:16
	global_load_dwordx4 v[120:123], v[210:211], off
	v_mov_b32_e32 v212, v12
	v_mov_b32_e32 v213, v161
	v_lshl_add_u64 v[212:213], v[16:17], 0, v[212:213]
	global_load_dwordx4 v[124:127], v[212:213], off offset:2048
	global_load_dwordx4 v[128:131], v[212:213], off offset:2064
	v_add_u32_e32 v222, 64, v13
	v_add_u32_e32 v223, s11, v222
	v_mad_i64_i32 v[214:215], s[0:1], v223, s65, v[14:15]
	v_lshl_add_u64 v[214:215], v[214:215], 0, s[2:3]
	v_lshl_add_u64 v[216:217], v[214:215], 0, v[160:161]
	global_load_dwordx4 v[132:135], v[216:217], off offset:1024
	global_load_dwordx4 v[136:139], v[216:217], off offset:1152
	v_lshl_or_b32 v218, v222, 6, v20
	v_mov_b32_e32 v219, v161
	v_lshl_add_u64 v[218:219], v[218:219], 3, s[4:5]
	global_load_dwordx4 v[140:143], v[218:219], off offset:48
	global_load_dwordx4 v[144:147], v[218:219], off offset:32
	global_load_dwordx4 v[148:151], v[218:219], off offset:16
	global_load_dwordx4 v[152:155], v[218:219], off
	v_mov_b32_e32 v220, v12
	v_mov_b32_e32 v221, v161
	v_lshl_add_u64 v[220:221], v[214:215], 0, v[220:221]
	global_load_dwordx4 v[156:159], v[220:221], off offset:2048
	global_load_dwordx4 v[204:207], v[220:221], off offset:2064
	v_add_u32_e32 v19, 32, v12
	s_waitcnt vmcnt(15)
	v_mov_b32_e32 v0, v100
	v_mov_b32_e32 v1, v101
	v_mov_b32_e32 v2, v102
	v_mov_b32_e32 v3, v103
	v_lshlrev_b32_e32 v26, 16, v0
	v_and_b32_e32 v27, 0xffff0000, v0
	v_lshlrev_b32_e32 v28, 16, v1
	v_and_b32_e32 v29, 0xffff0000, v1
	v_lshlrev_b32_e32 v30, 16, v2
	v_and_b32_e32 v31, 0xffff0000, v2
	v_lshlrev_b32_e32 v32, 16, v3
	v_and_b32_e32 v33, 0xffff0000, v3
	s_waitcnt vmcnt(14)
	v_mov_b32_e32 v0, v104
	v_mov_b32_e32 v1, v105
	v_mov_b32_e32 v2, v106
	v_mov_b32_e32 v3, v107
	v_lshlrev_b32_e32 v34, 16, v0
	v_and_b32_e32 v35, 0xffff0000, v0
	v_sub_u32_e32 v0, 0x7f, v13
	v_cvt_f32_i32_e32 v0, v0
	v_lshlrev_b32_e32 v36, 16, v1
	v_and_b32_e32 v37, 0xffff0000, v1
	v_lshlrev_b32_e32 v38, 16, v2
	v_mul_f32_e32 v0, v21, v0
	v_mul_f32_e32 v0, 0x3fb8aa3b, v0
	v_exp_f32_e32 v0, v0
	v_and_b32_e32 v39, 0xffff0000, v2
	v_lshlrev_b32_e32 v40, 16, v3
	v_and_b32_e32 v41, 0xffff0000, v3
	v_mul_f32_e32 v42, 0x3db504f3, v0
	v_lshl_or_b32 v0, v13, 6, v20
	v_ashrrev_i32_e32 v1, 31, v0
	v_lshl_add_u64 v[22:23], v[0:1], 3, s[4:5]
	s_nop 0
	s_waitcnt vmcnt(10)
; DI void unpack8(uint4 v, float* f) { f[0] = bflo(v.x); f[1] = bfhi(v.x); f[2] = bflo(v.y); f[3] = bfhi(v.y); f[4] = bflo(v.z); f[5] = bfhi(v.z); f[6] = bflo(v.w); f[7] = bfhi(v.w); }
; DI uint4 pack8(const float* f) { uint4 r; r.x = pk2(f[0], f[1]); r.y = pk2(f[2], f[3]); r.z = pk2(f[4], f[5]); r.w = pk2(f[6], f[7]); return r; }
; DI void ret_local_unit(const Params& p, int hf, int bl, int c, int hd, unsigned char* shm, int tid) {
;     ...
; #pragma unroll
;   for (int it = 0; it < 2; ++it) {
;     const int idx = tid + it * NTHR, j = idx >> 3, dg = idx & 7;
;     const bf16_t* base = projb + (size_t)(c * 128 + j) * NP;
;     float k1[8], k2[8]; unpack8(*(const uint4*)(base + C_RK + hd * 128 + dg * 8), k1); unpack8(*(const uint4*)(base + C_RK + hd * 128 + 64 + dg * 8), k2);
;     const float w = __expf(lg * (float)(127 - j)) * 0.08838834764831845f;
;     float o1[8], o2[8];
; #pragma unroll
;     for (int e = 0; e < 8; ++e) {
;       const float2 t = cs[j * 64 + dg * 8 + e];
;       o1[e] = (k1[e] * t.x - k2[e] * t.y) * w; o2[e] = (k1[e] * t.y + k2[e] * t.x) * w;
;     }
;     *(uint4*)(sK + j * LD + dg * 8) = pack8(o1); *(uint4*)(sK + j * LD + 64 + dg * 8) = pack8(o2);
;     *(uint4*)(sV + j * LD + dg * 16) = *(const uint4*)(base + C_RV + hd * 128 + dg * 16);
;     *(uint4*)(sV + j * LD + dg * 16 + 8) = *(const uint4*)(base + C_RV + hd * 128 + dg * 16 + 8);
;   }
;   __syncthreads();
	v_mov_b32_e32 v0, v108
	v_mov_b32_e32 v1, v109
	v_mov_b32_e32 v2, v110
	v_mov_b32_e32 v3, v111
	v_mov_b32_e32 v4, v112
	v_mov_b32_e32 v5, v113
	v_mov_b32_e32 v6, v114
	v_mov_b32_e32 v7, v115
	v_mov_b32_e32 v8, v116
	v_mov_b32_e32 v9, v117
	v_mov_b32_e32 v10, v118
	v_mov_b32_e32 v11, v119
	v_mov_b32_e32 v22, v120
	v_mov_b32_e32 v23, v121
	v_mov_b32_e32 v24, v122
	v_mov_b32_e32 v25, v123
	v_mul_f32_e32 v43, v23, v34
	v_mul_f32_e32 v23, v23, v26
	v_fmac_f32_e32 v23, v22, v34
	v_fma_f32 v43, v22, v26, -v43
	v_mul_f32_e32 v22, v42, v23
	v_mul_f32_e32 v23, v25, v35
	v_mul_f32_e32 v25, v25, v27
	v_fmac_f32_e32 v25, v24, v35
	v_fma_f32 v23, v24, v27, -v23
	v_mul_f32_e32 v24, v42, v25
	v_mul_f32_e32 v25, v9, v36
	v_mul_f32_e32 v9, v9, v28
	v_fmac_f32_e32 v9, v8, v36
	v_fma_f32 v25, v8, v28, -v25
	v_mul_f32_e32 v8, v42, v9
	v_mul_f32_e32 v9, v11, v37
	v_mul_f32_e32 v11, v11, v29
	v_fmac_f32_e32 v11, v10, v37
	v_fma_f32 v9, v10, v29, -v9
	v_mul_f32_e32 v10, v42, v11
	v_mul_f32_e32 v11, v5, v38
	v_mul_f32_e32 v5, v5, v30
	v_fmac_f32_e32 v5, v4, v38
	v_fma_f32 v11, v4, v30, -v11
	v_mul_f32_e32 v4, v42, v5
	v_mul_f32_e32 v5, v7, v39
	v_mul_f32_e32 v7, v7, v31
	v_fmac_f32_e32 v7, v6, v39
	v_fma_f32 v5, v6, v31, -v5
	v_mul_f32_e32 v6, v42, v7
	v_mul_f32_e32 v7, v1, v40
	v_mul_f32_e32 v1, v1, v32
	v_fma_f32 v7, v0, v32, -v7
	v_fmac_f32_e32 v1, v0, v40
	v_mul_f32_e32 v0, v3, v41
	v_fma_f32 v0, v2, v33, -v0
	v_mul_f32_e32 v27, v42, v0
	v_mul_f32_e32 v0, v3, v33
	v_mul_f32_e32 v7, v42, v7
	v_fmac_f32_e32 v0, v2, v41
	v_mul_f32_e32 v43, v42, v43
	v_mul_f32_e32 v23, v42, v23
	v_mul_f32_e32 v25, v42, v25
	v_mul_f32_e32 v9, v42, v9
	v_mul_f32_e32 v11, v42, v11
	v_mul_f32_e32 v5, v42, v5
	v_mul_f32_e32 v26, v42, v1
	v_mul_f32_e32 v28, v42, v0
	v_cvt_pk_bf16_f32 v0, v43, v23
	v_cvt_pk_bf16_f32 v1, v25, v9
	v_cvt_pk_bf16_f32 v2, v11, v5
	v_cvt_pk_bf16_f32 v3, v7, v27
	v_mul_lo_u32 v7, v13, s66
	v_add3_u32 v5, 32, v7, v160
	v_mov_b32_e32 v13, v161
	ds_write_b128 v5, v[0:3]
	v_cvt_pk_bf16_f32 v0, v22, v24
	v_cvt_pk_bf16_f32 v1, v8, v10
	v_cvt_pk_bf16_f32 v2, v4, v6
	v_cvt_pk_bf16_f32 v3, v26, v28
	ds_write_b128 v5, v[0:3] offset:128
	v_lshl_add_u64 v[4:5], v[16:17], 0, v[12:13]
	v_add_u32_e32 v6, v19, v7
	s_waitcnt vmcnt(9)
	v_mov_b32_e32 v0, v124
	v_mov_b32_e32 v1, v125
	v_mov_b32_e32 v2, v126
	v_mov_b32_e32 v3, v127
	ds_write_b128 v6, v[0:3] offset:34816
	s_waitcnt vmcnt(8)
	v_mov_b32_e32 v0, v128
	v_mov_b32_e32 v1, v129
	v_mov_b32_e32 v2, v130
	v_mov_b32_e32 v3, v131
	ds_write_b128 v6, v[0:3] offset:34832
	v_add_u32_e32 v0, 0x200, v18
	v_ashrrev_i32_e32 v24, 3, v0
	v_add_u32_e32 v0, s11, v24
	v_mad_i64_i32 v[0:1], s[0:1], v0, s65, v[14:15]
	v_lshl_add_u64 v[0:1], v[0:1], 0, s[2:3]
	v_lshl_add_u64 v[6:7], v[0:1], 0, v[160:161]
	s_and_b32 s0, s8, 0x3ff00
	s_lshl_b32 s1, s10, 2
	s_or_b32 s0, s1, s0
	s_or_b32 s0, s0, s9
	s_lshl_b32 s2, s0, 14
	s_lshl_b64 s[0:1], s[2:3], 1
	v_readlane_b32 s2, v253, 28
	s_add_u32 s0, s2, s0
	v_readlane_b32 s2, v253, 29
	s_addc_u32 s1, s2, s1
	s_waitcnt vmcnt(7)
	v_mov_b32_e32 v2, v132
	v_mov_b32_e32 v3, v133
	v_mov_b32_e32 v4, v134
	v_mov_b32_e32 v5, v135
	v_lshlrev_b32_e32 v25, 16, v2
	v_and_b32_e32 v26, 0xffff0000, v2
	v_lshlrev_b32_e32 v27, 16, v3
	v_and_b32_e32 v28, 0xffff0000, v3
	v_lshlrev_b32_e32 v29, 16, v4
	v_and_b32_e32 v30, 0xffff0000, v4
	v_lshlrev_b32_e32 v31, 16, v5
	v_and_b32_e32 v32, 0xffff0000, v5
	s_waitcnt vmcnt(6)
	v_mov_b32_e32 v2, v136
	v_mov_b32_e32 v3, v137
	v_mov_b32_e32 v4, v138
	v_mov_b32_e32 v5, v139
	v_lshlrev_b32_e32 v33, 16, v2
	v_and_b32_e32 v34, 0xffff0000, v2
	v_sub_u32_e32 v2, 0x7f, v24
	v_cvt_f32_i32_e32 v2, v2
	v_lshlrev_b32_e32 v35, 16, v3
	v_and_b32_e32 v36, 0xffff0000, v3
	v_lshlrev_b32_e32 v37, 16, v4
	v_mul_f32_e32 v2, v21, v2
	v_mul_f32_e32 v2, 0x3fb8aa3b, v2
	v_exp_f32_e32 v2, v2
	v_and_b32_e32 v38, 0xffff0000, v4
	v_lshlrev_b32_e32 v39, 16, v5
	v_and_b32_e32 v40, 0xffff0000, v5
	v_mul_f32_e32 v41, 0x3db504f3, v2
	v_lshl_or_b32 v2, v24, 6, v20
	v_ashrrev_i32_e32 v3, 31, v2
	v_lshl_add_u64 v[10:11], v[2:3], 3, s[4:5]
	s_waitcnt vmcnt(2)
	v_mov_b32_e32 v2, v140
	v_mov_b32_e32 v3, v141
	v_mov_b32_e32 v4, v142
	v_mov_b32_e32 v5, v143
	v_mov_b32_e32 v6, v144
	v_mov_b32_e32 v7, v145
	v_mov_b32_e32 v8, v146
	v_mov_b32_e32 v9, v147
	v_mov_b32_e32 v14, v148
	v_mov_b32_e32 v15, v149
	v_mov_b32_e32 v16, v150
	v_mov_b32_e32 v17, v151
	v_mov_b32_e32 v20, v152
	v_mov_b32_e32 v21, v153
	v_mov_b32_e32 v22, v154
	v_mov_b32_e32 v23, v155
	v_mul_f32_e32 v10, v21, v33
	v_mul_f32_e32 v11, v21, v25
	v_fma_f32 v10, v20, v25, -v10
	v_fmac_f32_e32 v11, v20, v33
	v_mul_f32_e32 v20, v23, v34
	v_mul_f32_e32 v21, v23, v26
	v_fma_f32 v20, v22, v26, -v20
	v_fmac_f32_e32 v21, v22, v34
	v_mul_f32_e32 v22, v15, v35
	v_mul_f32_e32 v15, v15, v27
	v_fmac_f32_e32 v15, v14, v35
	v_fma_f32 v22, v14, v27, -v22
	v_mul_f32_e32 v14, v41, v15
	v_mul_f32_e32 v15, v17, v36
	v_mul_f32_e32 v17, v17, v28
	v_fmac_f32_e32 v17, v16, v36
	v_fma_f32 v15, v16, v28, -v15
	v_mul_f32_e32 v16, v41, v17
	v_mul_f32_e32 v17, v7, v37
	v_mul_f32_e32 v7, v7, v29
	v_fmac_f32_e32 v7, v6, v37
	v_fma_f32 v17, v6, v29, -v17
	v_mul_f32_e32 v6, v41, v7
	v_mul_f32_e32 v7, v9, v38
	v_mul_f32_e32 v9, v9, v30
	v_fmac_f32_e32 v9, v8, v38
	v_fma_f32 v7, v8, v30, -v7
	v_mul_f32_e32 v8, v41, v9
	v_mul_f32_e32 v9, v3, v39
	v_mul_f32_e32 v3, v3, v31
	v_fma_f32 v9, v2, v31, -v9
	v_fmac_f32_e32 v3, v2, v39
	v_mul_f32_e32 v2, v5, v40
	v_fma_f32 v2, v4, v32, -v2
	v_mul_f32_e32 v25, v41, v2
	v_mul_f32_e32 v2, v5, v32
	v_mul_f32_e32 v7, v41, v7
	v_fmac_f32_e32 v2, v4, v40
	v_mul_f32_e32 v10, v41, v10
	v_mul_f32_e32 v20, v41, v20
	v_mul_f32_e32 v22, v41, v22
	v_mul_f32_e32 v15, v41, v15
	v_mul_f32_e32 v17, v41, v17
	v_mul_f32_e32 v9, v41, v9
	v_mul_f32_e32 v23, v41, v3
	v_mul_f32_e32 v26, v41, v2
	v_cvt_pk_bf16_f32 v2, v10, v20
	v_cvt_pk_bf16_f32 v3, v22, v15
	v_cvt_pk_bf16_f32 v4, v17, v7
	v_mul_lo_u32 v7, v24, s66
	v_cvt_pk_bf16_f32 v5, v9, v25
	v_add3_u32 v9, 32, v7, v160
	v_mul_f32_e32 v11, v41, v11
	v_mul_f32_e32 v21, v41, v21
	ds_write_b128 v9, v[2:5]
	v_cvt_pk_bf16_f32 v2, v11, v21
	v_cvt_pk_bf16_f32 v3, v14, v16
	v_cvt_pk_bf16_f32 v4, v6, v8
	v_cvt_pk_bf16_f32 v5, v23, v26
	ds_write_b128 v9, v[2:5] offset:128
	v_lshl_add_u64 v[4:5], v[0:1], 0, v[12:13]
	v_add_u32_e32 v6, v19, v7
	s_waitcnt vmcnt(1)
	v_mov_b32_e32 v0, v156
	v_mov_b32_e32 v1, v157
	v_mov_b32_e32 v2, v158
	v_mov_b32_e32 v3, v159
	ds_write_b128 v6, v[0:3] offset:34816
	v_ashrrev_i32_e32 v4, 6, v18
	v_and_b32_e32 v5, 15, v18
	v_lshlrev_b32_e32 v5, 7, v5
	s_waitcnt vmcnt(0)
	v_mov_b32_e32 v0, v204
	v_mov_b32_e32 v1, v205
	v_mov_b32_e32 v2, v206
	v_mov_b32_e32 v3, v207
	ds_write_b128 v6, v[0:3] offset:34832
	v_lshrrev_b32_e32 v0, 1, v18
	v_and_b32_e32 v160, 24, v0
	v_bfe_u32 v0, v18, 2, 2
	v_or_b32_e32 v0, v160, v0
	v_lshlrev_b32_e32 v1, 3, v18
	v_mul_u32_u24_e32 v0, 0x88, v0
	v_and_b32_e32 v1, 24, v1
	v_lshlrev_b32_e32 v0, 1, v0
	v_add3_u32 v6, 32, v1, v0
	v_lshl_add_u32 v7, v4, 5, v6
	s_waitcnt lgkmcnt(0)
	s_barrier
; DI f32x4 mmaT(bf16x8 a_m, bf16x8 b_n, f32x4 c) { return __builtin_amdgcn_mfma_f32_16x16x32_bf16(b_n, a_m, c, 0, 0, 0); }
; DI void ret_local_unit(const Params& p, int hf, int bl, int c, int hd, unsigned char* shm, int tid) {
;     ...
;   const int wid = tid >> 6, lane = tid & 63, fr = lane & 15, fq = lane >> 4;
;   f32x4 acc[8];
; #pragma unroll
;   for (int n = 0; n < 8; ++n) acc[n] = (f32x4){0.f, 0.f, 0.f, 0.f};
; #pragma unroll
;   for (int ks = 0; ks < 4; ++ks) {
;     const bf16x8 a = frag_tr(sV, LD, 32 * ks, 16 * wid, fr, fq);
; #pragma unroll
;     for (int n = 0; n < 8; ++n) acc[n] = mmaT(a, frag_tr(sK, LD, 32 * ks, 16 * n, fr, fq), acc[n]);
;   }
	ds_read_b64_tr_b16 v[0:1], v7 offset:34816
	ds_read_b64_tr_b16 v[2:3], v7 offset:35904
	ds_read_b64_tr_b16 v[10:11], v6 offset:1088
	ds_read_b64_tr_b16 v[8:9], v6
	ds_read_b64_tr_b16 v[12:13], v6 offset:32
	ds_read_b64_tr_b16 v[14:15], v6 offset:1120
	ds_read_b64_tr_b16 v[16:17], v6 offset:64
	ds_read_b64_tr_b16 v[18:19], v6 offset:1152
	ds_read_b64_tr_b16 v[20:21], v6 offset:96
	ds_read_b64_tr_b16 v[22:23], v6 offset:1184
	ds_read_b64_tr_b16 v[24:25], v6 offset:128
	ds_read_b64_tr_b16 v[26:27], v6 offset:1216
	ds_read_b64_tr_b16 v[28:29], v6 offset:160
	ds_read_b64_tr_b16 v[30:31], v6 offset:1248
	ds_read_b64_tr_b16 v[32:33], v6 offset:192
	ds_read_b64_tr_b16 v[34:35], v6 offset:1280
	ds_read_b64_tr_b16 v[36:37], v6 offset:224
	ds_read_b64_tr_b16 v[38:39], v6 offset:1312
	s_waitcnt lgkmcnt(14)
	v_mfma_f32_16x16x32_bf16 v[8:11], v[8:11], v[0:3], 0
	v_lshl_or_b32 v4, v4, 11, v5
	v_ashrrev_i32_e32 v5, 31, v4
	v_lshl_add_u64 v[4:5], v[4:5], 1, s[0:1]
	s_waitcnt lgkmcnt(12)
	v_mfma_f32_16x16x32_bf16 v[12:15], v[12:15], v[0:3], 0
	v_lshl_add_u64 v[4:5], v[4:5], 0, v[160:161]
	s_mov_b64 s[0:1], 0
	s_waitcnt lgkmcnt(10)
	v_mfma_f32_16x16x32_bf16 v[16:19], v[16:19], v[0:3], 0
	s_waitcnt lgkmcnt(8)
	v_mfma_f32_16x16x32_bf16 v[20:23], v[20:23], v[0:3], 0
	s_waitcnt lgkmcnt(6)
	v_mfma_f32_16x16x32_bf16 v[24:27], v[24:27], v[0:3], 0
	s_waitcnt lgkmcnt(4)
	v_mfma_f32_16x16x32_bf16 v[28:31], v[28:31], v[0:3], 0
	s_waitcnt lgkmcnt(2)
	v_mfma_f32_16x16x32_bf16 v[32:35], v[32:35], v[0:3], 0
	s_waitcnt lgkmcnt(0)
	v_mfma_f32_16x16x32_bf16 v[0:3], v[36:39], v[0:3], 0
	ds_read_b64_tr_b16 v[36:37], v7 offset:43520
	ds_read_b64_tr_b16 v[38:39], v7 offset:44608
	ds_read_b64_tr_b16 v[44:45], v6 offset:8704
	ds_read_b64_tr_b16 v[46:47], v6 offset:9792
	ds_read_b64_tr_b16 v[48:49], v6 offset:8736
	ds_read_b64_tr_b16 v[50:51], v6 offset:9824
	ds_read_b64_tr_b16 v[52:53], v6 offset:8768
	ds_read_b64_tr_b16 v[54:55], v6 offset:9856
	ds_read_b64_tr_b16 v[56:57], v6 offset:8800
	ds_read_b64_tr_b16 v[58:59], v6 offset:9888
	ds_read_b64_tr_b16 v[60:61], v6 offset:8832
	ds_read_b64_tr_b16 v[62:63], v6 offset:9920
	ds_read_b64_tr_b16 v[64:65], v6 offset:8864
	ds_read_b64_tr_b16 v[66:67], v6 offset:9952
	ds_read_b64_tr_b16 v[68:69], v6 offset:8896
	ds_read_b64_tr_b16 v[70:71], v6 offset:9984
	ds_read_b64_tr_b16 v[72:73], v6 offset:8928
	ds_read_b64_tr_b16 v[74:75], v6 offset:10016
	s_waitcnt lgkmcnt(14)
	v_mfma_f32_16x16x32_bf16 v[8:11], v[44:47], v[36:39], v[8:11]
	s_waitcnt lgkmcnt(12)
	v_mfma_f32_16x16x32_bf16 v[12:15], v[48:51], v[36:39], v[12:15]
	s_waitcnt lgkmcnt(10)
	v_mfma_f32_16x16x32_bf16 v[16:19], v[52:55], v[36:39], v[16:19]
	s_waitcnt lgkmcnt(8)
	v_mfma_f32_16x16x32_bf16 v[20:23], v[56:59], v[36:39], v[20:23]
	s_waitcnt lgkmcnt(6)
	v_mfma_f32_16x16x32_bf16 v[24:27], v[60:63], v[36:39], v[24:27]
	s_waitcnt lgkmcnt(4)
	v_mfma_f32_16x16x32_bf16 v[28:31], v[64:67], v[36:39], v[28:31]
	s_waitcnt lgkmcnt(2)
	v_mfma_f32_16x16x32_bf16 v[32:35], v[68:71], v[36:39], v[32:35]
	s_waitcnt lgkmcnt(0)
	v_mfma_f32_16x16x32_bf16 v[0:3], v[72:75], v[36:39], v[0:3]
	ds_read_b64_tr_b16 v[36:37], v7 offset:52224
	ds_read_b64_tr_b16 v[38:39], v7 offset:53312
	ds_read_b64_tr_b16 v[44:45], v6 offset:17408
	ds_read_b64_tr_b16 v[46:47], v6 offset:18496
	ds_read_b64_tr_b16 v[48:49], v6 offset:17440
	ds_read_b64_tr_b16 v[50:51], v6 offset:18528
	ds_read_b64_tr_b16 v[52:53], v6 offset:17472
	ds_read_b64_tr_b16 v[54:55], v6 offset:18560
	ds_read_b64_tr_b16 v[56:57], v6 offset:17504
	ds_read_b64_tr_b16 v[58:59], v6 offset:18592
	ds_read_b64_tr_b16 v[60:61], v6 offset:17536
	ds_read_b64_tr_b16 v[62:63], v6 offset:18624
	ds_read_b64_tr_b16 v[64:65], v6 offset:17568
	ds_read_b64_tr_b16 v[66:67], v6 offset:18656
	ds_read_b64_tr_b16 v[68:69], v6 offset:17600
	ds_read_b64_tr_b16 v[70:71], v6 offset:18688
	ds_read_b64_tr_b16 v[72:73], v6 offset:17632
	ds_read_b64_tr_b16 v[74:75], v6 offset:18720
	s_waitcnt lgkmcnt(14)
; DI unsigned pk2(float lo, float hi) { unsigned r; asm volatile("v_cvt_pk_bf16_f32 %0, %1, %2" : "=v"(r) : "v"(lo), "v"(hi)); return r; }
; DI f32x4 mmaT(bf16x8 a_m, bf16x8 b_n, f32x4 c) { return __builtin_amdgcn_mfma_f32_16x16x32_bf16(b_n, a_m, c, 0, 0, 0); }
; DI void ret_local_unit(const Params& p, int hf, int bl, int c, int hd, unsigned char* shm, int tid) {
;     ...
; #pragma unroll
;   for (int ks = 0; ks < 4; ++ks) {
;     const bf16x8 a = frag_tr(sV, LD, 32 * ks, 16 * wid, fr, fq);
; #pragma unroll
;     for (int n = 0; n < 8; ++n) acc[n] = mmaT(a, frag_tr(sK, LD, 32 * ks, 16 * n, fr, fq), acc[n]);
;   }
;   bf16_t* st = (bf16_t*)(wsb + WS_RST) + (size_t)((bl * 64 + c) * 4 + hd) * 16384;
; #pragma unroll
;   for (int n = 0; n < 8; ++n) { uint2 w; w.x = pk2(acc[n][0], acc[n][1]); w.y = pk2(acc[n][2], acc[n][3]); *(uint2*)(st + (16 * wid + fr) * 128 + 16 * n + 4 * fq) = w; }
;   __syncthreads();
	v_mfma_f32_16x16x32_bf16 v[8:11], v[44:47], v[36:39], v[8:11]
	s_waitcnt lgkmcnt(12)
	v_mfma_f32_16x16x32_bf16 v[12:15], v[48:51], v[36:39], v[12:15]
	s_waitcnt lgkmcnt(10)
	v_mfma_f32_16x16x32_bf16 v[16:19], v[52:55], v[36:39], v[16:19]
	s_waitcnt lgkmcnt(8)
	v_mfma_f32_16x16x32_bf16 v[20:23], v[56:59], v[36:39], v[20:23]
	s_waitcnt lgkmcnt(6)
	v_mfma_f32_16x16x32_bf16 v[24:27], v[60:63], v[36:39], v[24:27]
	s_waitcnt lgkmcnt(4)
	v_mfma_f32_16x16x32_bf16 v[28:31], v[64:67], v[36:39], v[28:31]
	s_waitcnt lgkmcnt(2)
	v_mfma_f32_16x16x32_bf16 v[32:35], v[68:71], v[36:39], v[32:35]
	s_waitcnt lgkmcnt(0)
	v_mfma_f32_16x16x32_bf16 v[0:3], v[72:75], v[36:39], v[0:3]
	ds_read_b64_tr_b16 v[36:37], v7 offset:60928
	ds_read_b64_tr_b16 v[38:39], v7 offset:62016
	ds_read_b64_tr_b16 v[40:41], v6 offset:26112
	ds_read_b64_tr_b16 v[42:43], v6 offset:27200
	s_waitcnt lgkmcnt(0)
	v_mfma_f32_16x16x32_bf16 v[8:11], v[40:43], v[36:39], v[8:11]
	ds_read_b64_tr_b16 v[40:41], v6 offset:26144
	ds_read_b64_tr_b16 v[42:43], v6 offset:27232
	s_waitcnt lgkmcnt(0)
	v_mfma_f32_16x16x32_bf16 v[12:15], v[40:43], v[36:39], v[12:15]
	ds_read_b64_tr_b16 v[40:41], v6 offset:26176
	ds_read_b64_tr_b16 v[42:43], v6 offset:27264
	s_waitcnt lgkmcnt(0)
	v_mfma_f32_16x16x32_bf16 v[16:19], v[40:43], v[36:39], v[16:19]
	ds_read_b64_tr_b16 v[40:41], v6 offset:26208
	ds_read_b64_tr_b16 v[42:43], v6 offset:27296
	s_waitcnt lgkmcnt(0)
	v_mfma_f32_16x16x32_bf16 v[20:23], v[40:43], v[36:39], v[20:23]
	ds_read_b64_tr_b16 v[40:41], v6 offset:26240
	ds_read_b64_tr_b16 v[42:43], v6 offset:27328
	s_waitcnt lgkmcnt(0)
	v_mfma_f32_16x16x32_bf16 v[24:27], v[40:43], v[36:39], v[24:27]
	ds_read_b64_tr_b16 v[40:41], v6 offset:26272
	ds_read_b64_tr_b16 v[42:43], v6 offset:27360
	s_waitcnt lgkmcnt(0)
	v_mfma_f32_16x16x32_bf16 v[28:31], v[40:43], v[36:39], v[28:31]
	ds_read_b64_tr_b16 v[40:41], v6 offset:26304
	ds_read_b64_tr_b16 v[42:43], v6 offset:27392
	s_waitcnt lgkmcnt(0)
	v_mfma_f32_16x16x32_bf16 v[32:35], v[40:43], v[36:39], v[32:35]
	ds_read_b64_tr_b16 v[40:41], v6 offset:26336
	ds_read_b64_tr_b16 v[42:43], v6 offset:27424
	v_cvt_pk_bf16_f32 v6, v8, v9
	v_cvt_pk_bf16_f32 v7, v10, v11
	global_store_dwordx2 v[4:5], v[6:7], off
	v_cvt_pk_bf16_f32 v6, v12, v13
	v_cvt_pk_bf16_f32 v7, v14, v15
	global_store_dwordx2 v[4:5], v[6:7], off offset:32
	v_cvt_pk_bf16_f32 v6, v16, v17
	v_cvt_pk_bf16_f32 v7, v18, v19
	global_store_dwordx2 v[4:5], v[6:7], off offset:64
	v_cvt_pk_bf16_f32 v6, v20, v21
	v_cvt_pk_bf16_f32 v7, v22, v23
	global_store_dwordx2 v[4:5], v[6:7], off offset:96
	v_cvt_pk_bf16_f32 v6, v24, v25
	v_cvt_pk_bf16_f32 v7, v26, v27
	s_waitcnt lgkmcnt(0)
	v_mfma_f32_16x16x32_bf16 v[0:3], v[40:43], v[36:39], v[0:3]
	global_store_dwordx2 v[4:5], v[6:7], off offset:128
	v_cvt_pk_bf16_f32 v6, v28, v29
	v_cvt_pk_bf16_f32 v7, v30, v31
	global_store_dwordx2 v[4:5], v[6:7], off offset:160
	v_cvt_pk_bf16_f32 v6, v32, v33
	v_cvt_pk_bf16_f32 v7, v34, v35
	global_store_dwordx2 v[4:5], v[6:7], off offset:192
	v_cvt_pk_bf16_f32 v0, v0, v1
	v_cvt_pk_bf16_f32 v1, v2, v3
	s_nop 4
	global_store_dwordx2 v[4:5], v[0:1], off offset:224
	s_barrier

; DI f32x4 mmaT(bf16x8 a_m, bf16x8 b_n, f32x4 c) { return __builtin_amdgcn_mfma_f32_16x16x32_bf16(b_n, a_m, c, 0, 0, 0); }
; DI void ssd_out_unit(const Params& p, int layer, int hf, int bl, int c, unsigned char* shm, int tid, bool dry = false) {
;     ...
; #pragma unroll
;     for (int it = 0; it < 4; ++it) {
;       const int idx = tid + it * NTHR, j = idx >> 4, ng = idx & 15;
;       *(uint4*)(sC + j * LD + ng * 8) = *(const uint4*)(xcb + (size_t)j * 1536 + 1280 + g * 128 + ng * 8);
;       *(uint4*)(sB + j * LD + ng * 8) = *(const uint4*)(xcb + (size_t)j * 1536 + 1024 + g * 128 + ng * 8);
;     }
;     __syncthreads();
;     f32x4 cbv[8];
;     {
;       bf16x8 ac[4];
; #pragma unroll
;       for (int ks = 0; ks < 4; ++ks) ac[ks] = ldf(sC, LD, 16 * wid, 32 * ks, fr, fq);
; #pragma unroll
;       for (int n = 0; n < 8; ++n) {
;         cbv[n] = (f32x4){0.f, 0.f, 0.f, 0.f};
;         if (n <= wid) {
; #pragma unroll
;           for (int ks = 0; ks < 4; ++ks) cbv[n] = mmaT(ac[ks], ldf(sB, LD, 16 * n, 32 * ks, fr, fq), cbv[n]);
;         }
;       }
;     }
.LBB0_503:
	s_lshl_b32 s2, s43, 8
	v_lshl_add_u64 v[4:5], v[90:91], 0, s[2:3]
	global_load_dwordx4 v[204:207], v[4:5], off offset:2560
	global_load_dwordx4 v[208:211], v[4:5], off offset:2048
	v_lshl_add_u64 v[4:5], v[94:95], 0, s[2:3]
	global_load_dwordx4 v[212:215], v[4:5], off offset:2560
	global_load_dwordx4 v[216:219], v[4:5], off offset:2048
	v_lshl_add_u64 v[4:5], v[98:99], 0, s[2:3]
	global_load_dwordx4 v[220:223], v[4:5], off offset:2560
	global_load_dwordx4 v[224:227], v[4:5], off offset:2048
	v_lshl_add_u64 v[4:5], v[102:103], 0, s[2:3]
	global_load_dwordx4 v[228:231], v[4:5], off offset:2560
	global_load_dwordx4 v[232:235], v[4:5], off offset:2048
	s_waitcnt lgkmcnt(0)
	s_barrier
	s_waitcnt vmcnt(0)
	ds_write_b128 v92, v[204:207]
	ds_write_b128 v93, v[208:211]
	ds_write_b128 v96, v[212:215]
	ds_write_b128 v97, v[216:219]
	ds_write_b128 v100, v[220:223]
	ds_write_b128 v101, v[224:227]
	ds_write_b128 v104, v[228:231]
	ds_write_b128 v105, v[232:235]
	v_add_u32_e32 v0, v121, v160
	s_waitcnt lgkmcnt(0)
	s_barrier
	ds_read_b128 v[44:47], v0
	ds_read_b128 v[40:43], v0 offset:64
	ds_read_b128 v[36:39], v0 offset:128
	ds_read_b128 v[32:35], v0 offset:192
	v_mov_b32_e32 v0, 0
	v_mov_b32_e32 v1, 0
	v_mov_b32_e32 v2, 0
	v_mov_b32_e32 v3, 0
	s_and_saveexec_b64 s[34:35], s[6:7]
	s_cbranch_execz .LBB0_505
	ds_read_b128 v[0:3], v133 offset:34816
	ds_read_b128 v[4:7], v133 offset:34880
	ds_read_b128 v[236:239], v133 offset:34944
	ds_read_b128 v[240:243], v133 offset:35008
	s_waitcnt lgkmcnt(3)
	v_mfma_f32_16x16x32_bf16 v[0:3], v[0:3], v[44:47], 0
	s_waitcnt lgkmcnt(2)
	v_mfma_f32_16x16x32_bf16 v[0:3], v[4:7], v[40:43], v[0:3]
	s_waitcnt lgkmcnt(1)
	v_mfma_f32_16x16x32_bf16 v[0:3], v[236:239], v[36:39], v[0:3]
	s_waitcnt lgkmcnt(0)
	v_mfma_f32_16x16x32_bf16 v[0:3], v[240:243], v[32:35], v[0:3]
.LBB0_505:
	s_or_b64 exec, exec, s[34:35]
	v_mov_b32_e32 v4, 0
	v_mov_b32_e32 v8, 0
	v_mov_b32_e32 v9, 0
	v_mov_b32_e32 v10, 0
	v_mov_b32_e32 v11, 0
	s_and_saveexec_b64 s[34:35], s[64:65]
	s_cbranch_execz .LBB0_507
	ds_read_b128 v[6:9], v133 offset:39168
	ds_read_b128 v[10:13], v133 offset:39232
	ds_read_b128 v[236:239], v133 offset:39296
	ds_read_b128 v[240:243], v133 offset:39360
	s_waitcnt lgkmcnt(3)
	v_mfma_f32_16x16x32_bf16 v[6:9], v[6:9], v[44:47], 0
	s_waitcnt lgkmcnt(2)
	v_mfma_f32_16x16x32_bf16 v[6:9], v[10:13], v[40:43], v[6:9]
	s_waitcnt lgkmcnt(1)
	v_mfma_f32_16x16x32_bf16 v[6:9], v[236:239], v[36:39], v[6:9]
	s_waitcnt lgkmcnt(0)
	v_mfma_f32_16x16x32_bf16 v[8:11], v[240:243], v[32:35], v[6:9]
.LBB0_507:
	s_or_b64 exec, exec, s[34:35]
	v_mov_b32_e32 v5, 0
	s_nop 2
	v_mov_b32_e32 v6, 0
	v_mov_b32_e32 v7, 0
	s_and_saveexec_b64 s[34:35], s[66:67]
	s_cbranch_execz .LBB0_509
	ds_read_b128 v[4:7], v133 offset:43520
	ds_read_b128 v[12:15], v133 offset:43584
	ds_read_b128 v[236:239], v133 offset:43648
	ds_read_b128 v[240:243], v133 offset:43712
	s_waitcnt lgkmcnt(3)
	v_mfma_f32_16x16x32_bf16 v[4:7], v[4:7], v[44:47], 0
	s_waitcnt lgkmcnt(2)
	v_mfma_f32_16x16x32_bf16 v[4:7], v[12:15], v[40:43], v[4:7]
	s_waitcnt lgkmcnt(1)
	v_mfma_f32_16x16x32_bf16 v[4:7], v[236:239], v[36:39], v[4:7]
	s_waitcnt lgkmcnt(0)
	v_mfma_f32_16x16x32_bf16 v[4:7], v[240:243], v[32:35], v[4:7]
.LBB0_509:
	s_or_b64 exec, exec, s[34:35]
	v_mov_b32_e32 v12, 0
	v_mov_b32_e32 v16, 0
	v_mov_b32_e32 v17, 0
	v_mov_b32_e32 v18, 0
	v_mov_b32_e32 v19, 0
	s_and_saveexec_b64 s[34:35], s[48:49]
	s_cbranch_execz .LBB0_511
	ds_read_b128 v[14:17], v133 offset:47872
	ds_read_b128 v[18:21], v133 offset:47936
	ds_read_b128 v[236:239], v133 offset:48000
	ds_read_b128 v[240:243], v133 offset:48064
	s_waitcnt lgkmcnt(3)
	v_mfma_f32_16x16x32_bf16 v[14:17], v[14:17], v[44:47], 0
	s_waitcnt lgkmcnt(2)
	v_mfma_f32_16x16x32_bf16 v[14:17], v[18:21], v[40:43], v[14:17]
	s_waitcnt lgkmcnt(1)
	v_mfma_f32_16x16x32_bf16 v[14:17], v[236:239], v[36:39], v[14:17]
	s_waitcnt lgkmcnt(0)
	v_mfma_f32_16x16x32_bf16 v[16:19], v[240:243], v[32:35], v[14:17]
.LBB0_511:
	s_or_b64 exec, exec, s[34:35]
	v_mov_b32_e32 v13, 0
	s_nop 2
	v_mov_b32_e32 v14, 0
	v_mov_b32_e32 v15, 0
	s_and_saveexec_b64 s[34:35], s[52:53]
	s_cbranch_execz .LBB0_513
	ds_read_b128 v[12:15], v133 offset:52224
	ds_read_b128 v[20:23], v133 offset:52288
	ds_read_b128 v[236:239], v133 offset:52352
	ds_read_b128 v[240:243], v133 offset:52416
	s_waitcnt lgkmcnt(3)
	v_mfma_f32_16x16x32_bf16 v[12:15], v[12:15], v[44:47], 0
	s_waitcnt lgkmcnt(2)
	v_mfma_f32_16x16x32_bf16 v[12:15], v[20:23], v[40:43], v[12:15]
	s_waitcnt lgkmcnt(1)
	v_mfma_f32_16x16x32_bf16 v[12:15], v[236:239], v[36:39], v[12:15]
	s_waitcnt lgkmcnt(0)
	v_mfma_f32_16x16x32_bf16 v[12:15], v[240:243], v[32:35], v[12:15]
.LBB0_513:
	s_or_b64 exec, exec, s[34:35]
	v_mov_b32_e32 v20, 0
	v_mov_b32_e32 v24, 0
	v_mov_b32_e32 v25, 0
	v_mov_b32_e32 v26, 0
	v_mov_b32_e32 v27, 0
	s_and_saveexec_b64 s[34:35], s[54:55]
	s_cbranch_execz .LBB0_515
	ds_read_b128 v[22:25], v133 offset:56576
	ds_read_b128 v[26:29], v133 offset:56640
	ds_read_b128 v[236:239], v133 offset:56704
	ds_read_b128 v[240:243], v133 offset:56768
	s_waitcnt lgkmcnt(3)
	v_mfma_f32_16x16x32_bf16 v[22:25], v[22:25], v[44:47], 0
	s_waitcnt lgkmcnt(2)
	v_mfma_f32_16x16x32_bf16 v[22:25], v[26:29], v[40:43], v[22:25]
	s_waitcnt lgkmcnt(1)
	v_mfma_f32_16x16x32_bf16 v[22:25], v[236:239], v[36:39], v[22:25]
	s_waitcnt lgkmcnt(0)
	v_mfma_f32_16x16x32_bf16 v[24:27], v[240:243], v[32:35], v[22:25]
.LBB0_515:
	s_or_b64 exec, exec, s[34:35]
	v_mov_b32_e32 v21, 0
	s_nop 2
	v_mov_b32_e32 v22, 0
	v_mov_b32_e32 v23, 0
	s_and_saveexec_b64 s[34:35], s[56:57]
	s_cbranch_execz .LBB0_517
	ds_read_b128 v[20:23], v133 offset:60928
	ds_read_b128 v[28:31], v133 offset:60992
	ds_read_b128 v[236:239], v133 offset:61056
	ds_read_b128 v[240:243], v133 offset:61120
	s_waitcnt lgkmcnt(3)
	v_mfma_f32_16x16x32_bf16 v[20:23], v[20:23], v[44:47], 0
	s_waitcnt lgkmcnt(2)
	v_mfma_f32_16x16x32_bf16 v[20:23], v[28:31], v[40:43], v[20:23]
	s_waitcnt lgkmcnt(1)
	v_mfma_f32_16x16x32_bf16 v[20:23], v[236:239], v[36:39], v[20:23]
	s_waitcnt lgkmcnt(0)
	v_mfma_f32_16x16x32_bf16 v[20:23], v[240:243], v[32:35], v[20:23]
